# odd XCDs also do their deferred weight-transpose / p->bf16 share right after the P0 barrier (before P1) instead of inside P2
# baseline (speedup 1.0000x reference)
.Lflag_done:
	s_bitcmp1_b32 s2, 0
	s_cbranch_scc0 .Lp1_go
	s_or_b32 s99, s99, 0x44
	s_branch .Lp0b_call

.LBB0_256:
	s_mov_b32 s98, 0
	s_bitcmp1_b32 s2, 0
	s_cbranch_scc0 .Lp2i_done
	s_movk_i32 s98, 0x1000
